# barrier invalidate moved to wave 1 of every workgroup (issued and waited for beside thread 0's protocol), thread 0 issues none
# baseline (speedup 1.0000x reference)
; __device__ __forceinline__ void xcd_barrier(const XcdBarrier& b) {
;     asm volatile("s_waitcnt vmcnt(0)" ::: "memory");
;     __syncthreads();
;     if (threadIdx.x == 0) {
;         unsigned* bar = b.bar;
;         __builtin_amdgcn_s_waitcnt(0);
;         unsigned nloc = b.st[0], nx = b.st[1];
;         if (nloc == 0u) { xcd_barrier_complete(bar, b.x, nloc, nx); b.st[0] = nloc; b.st[1] = nx; }
.LBB0_32:
	s_cmp_gt_i32 s75, 1
	s_cselect_b64 s[2:3], -1, 0
	s_and_b64 s[0:1], s[0:1], s[2:3]
	s_andn2_b64 vcc, exec, s[0:1]
	s_cbranch_vccnz .LBB0_86
	s_waitcnt vmcnt(0)
	s_waitcnt lgkmcnt(0)
	s_barrier
	v_readfirstlane_b32 s4, v188
	s_lshr_b32 s4, s4, 6
	s_cmp_eq_u32 s4, 1
	s_cbranch_scc0 .Lmy_w1_0
	buffer_inv sc1
	s_waitcnt vmcnt(0)
.Lmy_w1_0:
	s_mov_b64 s[0:1], exec
	v_readlane_b32 s4, v254, 9
	v_readlane_b32 s5, v254, 10
	s_and_b64 s[4:5], s[0:1], s[4:5]
	s_mov_b64 exec, s[4:5]
	s_cbranch_execz .LBB0_85
	s_add_i32 s4, 0, 0x26700
	s_waitcnt vmcnt(35)
	v_mov_b32_e32 v0, s4
	s_waitcnt vmcnt(0) expcnt(0) lgkmcnt(0)
	ds_read_b32 v2, v0
	s_add_i32 s4, 0, 0x26704
	v_mov_b32_e32 v0, s4
	ds_read_b32 v0, v0
	s_waitcnt lgkmcnt(1)
	v_cmp_ne_u32_e32 vcc, 0, v2
	s_cbranch_vccnz .LBB0_49
	v_readlane_b32 s4, v254, 8
	s_mul_i32 s18, s85, s4
	s_add_u32 s4, s72, 0x1000
	s_addc_u32 s5, s73, 0
	s_add_u32 s6, s72, 0x1100
	s_addc_u32 s7, s73, 0
	s_add_u32 s8, s72, 0x1200
	s_addc_u32 s9, s73, 0
	s_add_u32 s10, s72, 0x1300
	s_mul_i32 s18, s18, s84
	s_addc_u32 s11, s73, 0
	s_mov_b32 s19, 1
	v_mov_b32_e32 v16, 0
	s_branch .LBB0_37

; __device__ __forceinline__ unsigned xb_add(unsigned* p, unsigned v) { return __hip_atomic_fetch_add(p, v, __ATOMIC_RELAXED, __HIP_MEMORY_SCOPE_AGENT); }
; __device__ __forceinline__ void xcd_barrier(const XcdBarrier& b) {
;     ...
;         if (old + 1u == (gen + 1u) * nloc) {
;             __builtin_amdgcn_fence(__ATOMIC_RELEASE, "agent");
;             asm volatile("s_waitcnt vmcnt(0)" ::: "memory");
;             const unsigned og = xb_add(&bar[XB_TOP], 1u);
;             const unsigned tg = og / nx;
;             if (og + 1u == (tg + 1u) * nx) xb_add(&bar[XB_TOPGEN], 1u);
.LBB0_64:
	s_or_b64 exec, exec, s[8:9]
	s_waitcnt vmcnt(0)
	s_waitcnt vmcnt(0)
.LBB0_65:
	s_andn2_saveexec_b64 s[6:7], s[6:7]
	s_cbranch_execz .LBB0_85
	s_mov_b64 s[6:7], exec
	buffer_wbl2 sc1
	s_waitcnt lgkmcnt(0)
	s_waitcnt vmcnt(0)
	v_mbcnt_lo_u32_b32 v1, s6, 0
	v_mbcnt_hi_u32_b32 v1, s7, v1
	v_cmp_eq_u32_e32 vcc, 0, v1
	s_and_saveexec_b64 s[8:9], vcc
	s_cbranch_execz .LBB0_68
	s_bcnt1_i32_b64 s6, s[6:7]
	v_mov_b32_e32 v2, 0x3000
	v_mov_b32_e32 v3, s6
	global_atomic_add v2, v2, v3, s[72:73] offset:1024 sc0

; __device__ __forceinline__ unsigned xb_ld(unsigned* p)              { return __hip_atomic_load(p, __ATOMIC_RELAXED, __HIP_MEMORY_SCOPE_AGENT); }
; __device__ __forceinline__ unsigned xb_add(unsigned* p, unsigned v) { return __hip_atomic_fetch_add(p, v, __ATOMIC_RELAXED, __HIP_MEMORY_SCOPE_AGENT); }
; #define XB_SPIN(cond, bar) do { unsigned _sp = 0; while (cond) { __builtin_amdgcn_s_sleep(1); \
;     if ((++_sp & 255u) == 0u) { if (xb_ld(&(bar)[XB_TMO])) break; if (_sp > XB_SPIN_CAP) { atomicAdd(&(bar)[XB_TMO], 1u); break; } } } } while (0)
; __device__ __forceinline__ void xcd_barrier(const XcdBarrier& b) {
;     asm volatile("s_waitcnt vmcnt(0)" ::: "memory");
;     __syncthreads();
;     if (threadIdx.x == 0) {
;         unsigned* bar = b.bar;
;         __builtin_amdgcn_s_waitcnt(0);
;         unsigned nloc = b.st[0], nx = b.st[1];
;         if (nloc == 0u) { xcd_barrier_complete(bar, b.x, nloc, nx); b.st[0] = nloc; b.st[1] = nx; }
;         const unsigned old = xb_add(&bar[XB_XSUB(b.x)], 1u);
;         const unsigned gen = old / nloc;
;         if (old + 1u == (gen + 1u) * nloc) {
;             __builtin_amdgcn_fence(__ATOMIC_RELEASE, "agent");
;             asm volatile("s_waitcnt vmcnt(0)" ::: "memory");
;             const unsigned og = xb_add(&bar[XB_TOP], 1u);
;             const unsigned tg = og / nx;
;             if (og + 1u == (tg + 1u) * nx) xb_add(&bar[XB_TOPGEN], 1u);
;             else XB_SPIN(xb_ld(&bar[XB_TOPGEN]) == tg, bar);
;             __builtin_amdgcn_fence(__ATOMIC_ACQUIRE, "agent");
;             xb_add(&bar[XB_XGEN(b.x)], 1u);
;             asm volatile("s_waitcnt vmcnt(0)" ::: "memory");
;         } else {
;             XB_SPIN(xb_ld(&bar[XB_XGEN(b.x)]) == gen, bar);
;             __builtin_amdgcn_fence(__ATOMIC_ACQUIRE, "agent");
;             asm volatile("s_waitcnt vmcnt(0)" ::: "memory");
;         }
.LBB0_157:
	s_cmp_gt_i32 s75, 2
	s_cselect_b64 s[0:1], -1, 0
	s_and_b64 s[2:3], s[4:5], s[0:1]
	s_andn2_b64 vcc, exec, s[2:3]
	s_cbranch_vccnz .LBB0_211
	s_waitcnt vmcnt(0)
	s_waitcnt vmcnt(0) lgkmcnt(0)
	s_barrier
	v_readfirstlane_b32 s4, v188
	s_lshr_b32 s4, s4, 6
	s_cmp_eq_u32 s4, 1
	s_cbranch_scc0 .Lmy_w1_1
	buffer_inv sc1
	s_waitcnt vmcnt(0)
.Lmy_w1_1:
	s_mov_b64 s[2:3], exec
	v_readlane_b32 s4, v254, 9
	v_readlane_b32 s5, v254, 10
	s_and_b64 s[4:5], s[2:3], s[4:5]
	s_mov_b64 exec, s[4:5]
	s_cbranch_execz .LBB0_210
	s_cmp_eq_u32 s74, 1
	s_cbranch_scc1 .Lmy_fb_1_orig
	s_add_i32 s4, 0, 0x26700
	v_mov_b32_e32 v0, s4
	ds_read2_b32 v[2:3], v0 offset1:1
	s_lshl_b32 s4, s88, 8
	s_add_u32 s4, s72, s4
	s_addc_u32 s5, s73, 0
	v_mov_b32_e32 v4, 0x1000
	v_mov_b32_e32 v5, 1
	global_atomic_add v4, v4, v5, s[4:5] offset:1024 sc0
	s_sub_i32 s6, 2, s74
	s_waitcnt lgkmcnt(0)
	v_readfirstlane_b32 s7, v2
	v_readfirstlane_b32 s8, v3
	s_mul_i32 s7, s7, s6
	s_add_i32 s6, s6, -1
	s_mul_i32 s8, s8, s6
	s_add_i32 s8, s8, 1
	v_mov_b32_e32 v6, 0x2000
	s_waitcnt vmcnt(0)
	v_readfirstlane_b32 s10, v4
	s_add_i32 s10, s10, 1
	s_cmp_lg_u32 s10, s7
	s_cbranch_scc1 .Lmy_fb_1_wait
	buffer_wbl2 sc1
	s_mov_b64 s[10:11], exec
	s_mov_b64 exec, 0xffff
	v_mbcnt_lo_u32_b32 v7, -1, 0
	v_lshlrev_b32_e32 v7, 8, v7
	v_add_u32_e32 v7, 0x2400, v7
	v_mov_b32_e32 v8, 1
	s_waitcnt vmcnt(0)
	global_atomic_add v7, v8, s[72:73]
	s_mov_b64 exec, s[10:11]
.Lmy_fb_1_wait:
	s_mov_b32 s11, 0

; __device__ __forceinline__ unsigned xb_ld(unsigned* p)              { return __hip_atomic_load(p, __ATOMIC_RELAXED, __HIP_MEMORY_SCOPE_AGENT); }
; __device__ __forceinline__ unsigned xb_add(unsigned* p, unsigned v) { return __hip_atomic_fetch_add(p, v, __ATOMIC_RELAXED, __HIP_MEMORY_SCOPE_AGENT); }
; #define XB_SPIN(cond, bar) do { unsigned _sp = 0; while (cond) { __builtin_amdgcn_s_sleep(1); \
;     if ((++_sp & 255u) == 0u) { if (xb_ld(&(bar)[XB_TMO])) break; if (_sp > XB_SPIN_CAP) { atomicAdd(&(bar)[XB_TMO], 1u); break; } } } } while (0)
; __device__ __forceinline__ void xcd_barrier(const XcdBarrier& b) {
;     asm volatile("s_waitcnt vmcnt(0)" ::: "memory");
;     __syncthreads();
;     if (threadIdx.x == 0) {
;         unsigned* bar = b.bar;
;         __builtin_amdgcn_s_waitcnt(0);
;         unsigned nloc = b.st[0], nx = b.st[1];
;         if (nloc == 0u) { xcd_barrier_complete(bar, b.x, nloc, nx); b.st[0] = nloc; b.st[1] = nx; }
;         const unsigned old = xb_add(&bar[XB_XSUB(b.x)], 1u);
;         const unsigned gen = old / nloc;
;         if (old + 1u == (gen + 1u) * nloc) {
;             __builtin_amdgcn_fence(__ATOMIC_RELEASE, "agent");
;             asm volatile("s_waitcnt vmcnt(0)" ::: "memory");
;             const unsigned og = xb_add(&bar[XB_TOP], 1u);
;             const unsigned tg = og / nx;
;             if (og + 1u == (tg + 1u) * nx) xb_add(&bar[XB_TOPGEN], 1u);
;             else XB_SPIN(xb_ld(&bar[XB_TOPGEN]) == tg, bar);
;             __builtin_amdgcn_fence(__ATOMIC_ACQUIRE, "agent");
;             xb_add(&bar[XB_XGEN(b.x)], 1u);
;             asm volatile("s_waitcnt vmcnt(0)" ::: "memory");
;         } else {
;             XB_SPIN(xb_ld(&bar[XB_XGEN(b.x)]) == gen, bar);
;             __builtin_amdgcn_fence(__ATOMIC_ACQUIRE, "agent");
;             asm volatile("s_waitcnt vmcnt(0)" ::: "memory");
;         }
.LBB0_723:
	s_cmp_gt_i32 s75, 3
	s_cselect_b64 s[0:1], -1, 0
	s_and_b64 s[2:3], s[2:3], s[0:1]
	s_andn2_b64 vcc, exec, s[2:3]
	s_cbranch_vccnz .LBB0_777
	s_waitcnt vmcnt(0)
	s_waitcnt vmcnt(0) lgkmcnt(0)
	s_barrier
	v_readfirstlane_b32 s4, v188
	s_lshr_b32 s4, s4, 6
	s_cmp_eq_u32 s4, 1
	s_cbranch_scc0 .Lmy_w1_2
	buffer_inv sc1
	s_waitcnt vmcnt(0)
.Lmy_w1_2:
	s_mov_b64 s[2:3], exec
	v_readlane_b32 s4, v254, 9
	v_readlane_b32 s5, v254, 10
	s_and_b64 s[4:5], s[2:3], s[4:5]
	s_mov_b64 exec, s[4:5]
	s_cbranch_execz .LBB0_776
	s_cmp_eq_u32 s74, 2
	s_cbranch_scc1 .Lmy_fb_2_orig
	s_add_i32 s4, 0, 0x26700
	v_mov_b32_e32 v0, s4
	ds_read2_b32 v[2:3], v0 offset1:1
	s_lshl_b32 s4, s88, 8
	s_add_u32 s4, s72, s4
	s_addc_u32 s5, s73, 0
	v_mov_b32_e32 v4, 0x1000
	v_mov_b32_e32 v5, 1
	global_atomic_add v4, v4, v5, s[4:5] offset:1024 sc0
	s_sub_i32 s6, 3, s74
	s_waitcnt lgkmcnt(0)
	v_readfirstlane_b32 s7, v2
	v_readfirstlane_b32 s8, v3
	s_mul_i32 s7, s7, s6
	s_add_i32 s6, s6, -1
	s_mul_i32 s8, s8, s6
	s_add_i32 s8, s8, 1
	v_mov_b32_e32 v6, 0x2000
	s_waitcnt vmcnt(0)
	v_readfirstlane_b32 s10, v4
	s_add_i32 s10, s10, 1
	s_cmp_lg_u32 s10, s7
	s_cbranch_scc1 .Lmy_fb_2_wait
	buffer_wbl2 sc1
	s_mov_b64 s[10:11], exec
	s_mov_b64 exec, 0xffff
	v_mbcnt_lo_u32_b32 v7, -1, 0
	v_lshlrev_b32_e32 v7, 8, v7
	v_add_u32_e32 v7, 0x2400, v7
	v_mov_b32_e32 v8, 1
	s_waitcnt vmcnt(0)
	global_atomic_add v7, v8, s[72:73]
	s_mov_b64 exec, s[10:11]

; __device__ __forceinline__ unsigned xb_ld(unsigned* p)              { return __hip_atomic_load(p, __ATOMIC_RELAXED, __HIP_MEMORY_SCOPE_AGENT); }
; __device__ __forceinline__ unsigned xb_add(unsigned* p, unsigned v) { return __hip_atomic_fetch_add(p, v, __ATOMIC_RELAXED, __HIP_MEMORY_SCOPE_AGENT); }
; #define XB_SPIN(cond, bar) do { unsigned _sp = 0; while (cond) { __builtin_amdgcn_s_sleep(1); \
;     if ((++_sp & 255u) == 0u) { if (xb_ld(&(bar)[XB_TMO])) break; if (_sp > XB_SPIN_CAP) { atomicAdd(&(bar)[XB_TMO], 1u); break; } } } } while (0)
; __device__ __forceinline__ void xcd_barrier(const XcdBarrier& b) {
;     asm volatile("s_waitcnt vmcnt(0)" ::: "memory");
;     __syncthreads();
;     if (threadIdx.x == 0) {
;         unsigned* bar = b.bar;
;         __builtin_amdgcn_s_waitcnt(0);
;         unsigned nloc = b.st[0], nx = b.st[1];
;         if (nloc == 0u) { xcd_barrier_complete(bar, b.x, nloc, nx); b.st[0] = nloc; b.st[1] = nx; }
;         const unsigned old = xb_add(&bar[XB_XSUB(b.x)], 1u);
;         const unsigned gen = old / nloc;
;         if (old + 1u == (gen + 1u) * nloc) {
;             __builtin_amdgcn_fence(__ATOMIC_RELEASE, "agent");
;             asm volatile("s_waitcnt vmcnt(0)" ::: "memory");
;             const unsigned og = xb_add(&bar[XB_TOP], 1u);
;             const unsigned tg = og / nx;
;             if (og + 1u == (tg + 1u) * nx) xb_add(&bar[XB_TOPGEN], 1u);
;             else XB_SPIN(xb_ld(&bar[XB_TOPGEN]) == tg, bar);
;             __builtin_amdgcn_fence(__ATOMIC_ACQUIRE, "agent");
;             xb_add(&bar[XB_XGEN(b.x)], 1u);
;             asm volatile("s_waitcnt vmcnt(0)" ::: "memory");
;         } else {
;             XB_SPIN(xb_ld(&bar[XB_XGEN(b.x)]) == gen, bar);
;             __builtin_amdgcn_fence(__ATOMIC_ACQUIRE, "agent");
;             asm volatile("s_waitcnt vmcnt(0)" ::: "memory");
;         }
.LBB0_808:
	s_cmp_gt_i32 s75, 4
	s_cselect_b64 s[2:3], -1, 0
	s_and_b64 s[0:1], s[0:1], s[2:3]
	s_andn2_b64 vcc, exec, s[0:1]
	s_cbranch_vccnz .LBB0_862
	s_waitcnt vmcnt(0)
	s_waitcnt vmcnt(0) lgkmcnt(0)
	s_barrier
	v_readfirstlane_b32 s4, v188
	s_lshr_b32 s4, s4, 6
	s_cmp_eq_u32 s4, 1
	s_cbranch_scc0 .Lmy_w1_3
	buffer_inv sc1
	s_waitcnt vmcnt(0)
.Lmy_w1_3:
	s_mov_b64 s[0:1], exec
	v_readlane_b32 s4, v254, 9
	v_readlane_b32 s5, v254, 10
	s_and_b64 s[4:5], s[0:1], s[4:5]
	s_mov_b64 exec, s[4:5]
	s_cbranch_execz .LBB0_861
	s_cmp_eq_u32 s74, 3
	s_cbranch_scc1 .Lmy_fb_3_orig
	s_add_i32 s4, 0, 0x26700
	v_mov_b32_e32 v0, s4
	ds_read2_b32 v[2:3], v0 offset1:1
	s_lshl_b32 s4, s88, 8
	s_add_u32 s4, s72, s4
	s_addc_u32 s5, s73, 0
	v_mov_b32_e32 v4, 0x1000
	v_mov_b32_e32 v5, 1
	global_atomic_add v4, v4, v5, s[4:5] offset:1024 sc0
	s_sub_i32 s6, 4, s74
	s_waitcnt lgkmcnt(0)
	v_readfirstlane_b32 s7, v2
	v_readfirstlane_b32 s8, v3
	s_mul_i32 s7, s7, s6
	s_add_i32 s6, s6, -1
	s_mul_i32 s8, s8, s6
	s_add_i32 s8, s8, 1
	v_mov_b32_e32 v6, 0x2000
	s_waitcnt vmcnt(0)
	v_readfirstlane_b32 s10, v4
	s_add_i32 s10, s10, 1
	s_cmp_lg_u32 s10, s7
	s_cbranch_scc1 .Lmy_fb_3_wait
	buffer_wbl2 sc1
	s_mov_b64 s[10:11], exec
	s_mov_b64 exec, 0xffff
	v_mbcnt_lo_u32_b32 v7, -1, 0
	v_lshlrev_b32_e32 v7, 8, v7
	v_add_u32_e32 v7, 0x2400, v7
	v_mov_b32_e32 v8, 1
	s_waitcnt vmcnt(0)
	global_atomic_add v7, v8, s[72:73]
	s_mov_b64 exec, s[10:11]

; __device__ __forceinline__ unsigned xb_ld(unsigned* p)              { return __hip_atomic_load(p, __ATOMIC_RELAXED, __HIP_MEMORY_SCOPE_AGENT); }
; __device__ __forceinline__ unsigned xb_add(unsigned* p, unsigned v) { return __hip_atomic_fetch_add(p, v, __ATOMIC_RELAXED, __HIP_MEMORY_SCOPE_AGENT); }
; #define XB_SPIN(cond, bar) do { unsigned _sp = 0; while (cond) { __builtin_amdgcn_s_sleep(1); \
;     if ((++_sp & 255u) == 0u) { if (xb_ld(&(bar)[XB_TMO])) break; if (_sp > XB_SPIN_CAP) { atomicAdd(&(bar)[XB_TMO], 1u); break; } } } } while (0)
; __device__ __forceinline__ void xcd_barrier(const XcdBarrier& b) {
;     asm volatile("s_waitcnt vmcnt(0)" ::: "memory");
;     __syncthreads();
;     if (threadIdx.x == 0) {
;         unsigned* bar = b.bar;
;         __builtin_amdgcn_s_waitcnt(0);
;         unsigned nloc = b.st[0], nx = b.st[1];
;         if (nloc == 0u) { xcd_barrier_complete(bar, b.x, nloc, nx); b.st[0] = nloc; b.st[1] = nx; }
;         const unsigned old = xb_add(&bar[XB_XSUB(b.x)], 1u);
;         const unsigned gen = old / nloc;
;         if (old + 1u == (gen + 1u) * nloc) {
;             __builtin_amdgcn_fence(__ATOMIC_RELEASE, "agent");
;             asm volatile("s_waitcnt vmcnt(0)" ::: "memory");
;             const unsigned og = xb_add(&bar[XB_TOP], 1u);
;             const unsigned tg = og / nx;
;             if (og + 1u == (tg + 1u) * nx) xb_add(&bar[XB_TOPGEN], 1u);
;             else XB_SPIN(xb_ld(&bar[XB_TOPGEN]) == tg, bar);
;             __builtin_amdgcn_fence(__ATOMIC_ACQUIRE, "agent");
;             xb_add(&bar[XB_XGEN(b.x)], 1u);
;             asm volatile("s_waitcnt vmcnt(0)" ::: "memory");
;         } else {
;             XB_SPIN(xb_ld(&bar[XB_XGEN(b.x)]) == gen, bar);
;             __builtin_amdgcn_fence(__ATOMIC_ACQUIRE, "agent");
;             asm volatile("s_waitcnt vmcnt(0)" ::: "memory");
;         }
.LBB0_905:
	s_cmp_gt_i32 s75, 5
	s_cselect_b64 s[2:3], -1, 0
	s_and_b64 s[0:1], s[0:1], s[2:3]
	s_andn2_b64 vcc, exec, s[0:1]
	s_cbranch_vccnz .LBB0_959
	s_waitcnt vmcnt(0)
	s_waitcnt vmcnt(0) lgkmcnt(0)
	s_barrier
	v_readfirstlane_b32 s4, v188
	s_lshr_b32 s4, s4, 6
	s_cmp_eq_u32 s4, 1
	s_cbranch_scc0 .Lmy_w1_4
	buffer_inv sc1
	s_waitcnt vmcnt(0)
.Lmy_w1_4:
	s_mov_b64 s[0:1], exec
	v_readlane_b32 s4, v254, 9
	v_readlane_b32 s5, v254, 10
	s_and_b64 s[4:5], s[0:1], s[4:5]
	s_mov_b64 exec, s[4:5]
	s_cbranch_execz .LBB0_958
	s_cmp_eq_u32 s74, 4
	s_cbranch_scc1 .Lmy_fb_4_orig
	s_add_i32 s4, 0, 0x26700
	v_mov_b32_e32 v0, s4
	ds_read2_b32 v[2:3], v0 offset1:1
	s_lshl_b32 s4, s88, 8
	s_add_u32 s4, s72, s4
	s_addc_u32 s5, s73, 0
	v_mov_b32_e32 v4, 0x1000
	v_mov_b32_e32 v5, 1
	global_atomic_add v4, v4, v5, s[4:5] offset:1024 sc0
	s_sub_i32 s6, 5, s74
	s_waitcnt lgkmcnt(0)
	v_readfirstlane_b32 s7, v2
	v_readfirstlane_b32 s8, v3
	s_mul_i32 s7, s7, s6
	s_add_i32 s6, s6, -1
	s_mul_i32 s8, s8, s6
	s_add_i32 s8, s8, 1
	v_mov_b32_e32 v6, 0x2000
	s_waitcnt vmcnt(0)
	v_readfirstlane_b32 s10, v4
	s_add_i32 s10, s10, 1
	s_cmp_lg_u32 s10, s7
	s_cbranch_scc1 .Lmy_fb_4_wait
	buffer_wbl2 sc1
	s_mov_b64 s[10:11], exec
	s_mov_b64 exec, 0xffff
	v_mbcnt_lo_u32_b32 v7, -1, 0
	v_lshlrev_b32_e32 v7, 8, v7
	v_add_u32_e32 v7, 0x2400, v7
	v_mov_b32_e32 v8, 1
	s_waitcnt vmcnt(0)
	global_atomic_add v7, v8, s[72:73]
	s_mov_b64 exec, s[10:11]

; __device__ __forceinline__ unsigned xb_ld(unsigned* p)              { return __hip_atomic_load(p, __ATOMIC_RELAXED, __HIP_MEMORY_SCOPE_AGENT); }
; __device__ __forceinline__ unsigned xb_add(unsigned* p, unsigned v) { return __hip_atomic_fetch_add(p, v, __ATOMIC_RELAXED, __HIP_MEMORY_SCOPE_AGENT); }
; #define XB_SPIN(cond, bar) do { unsigned _sp = 0; while (cond) { __builtin_amdgcn_s_sleep(1); \
;     if ((++_sp & 255u) == 0u) { if (xb_ld(&(bar)[XB_TMO])) break; if (_sp > XB_SPIN_CAP) { atomicAdd(&(bar)[XB_TMO], 1u); break; } } } } while (0)
; __device__ __forceinline__ void xcd_barrier(const XcdBarrier& b) {
;     asm volatile("s_waitcnt vmcnt(0)" ::: "memory");
;     __syncthreads();
;     if (threadIdx.x == 0) {
;         unsigned* bar = b.bar;
;         __builtin_amdgcn_s_waitcnt(0);
;         unsigned nloc = b.st[0], nx = b.st[1];
;         if (nloc == 0u) { xcd_barrier_complete(bar, b.x, nloc, nx); b.st[0] = nloc; b.st[1] = nx; }
;         const unsigned old = xb_add(&bar[XB_XSUB(b.x)], 1u);
;         const unsigned gen = old / nloc;
;         if (old + 1u == (gen + 1u) * nloc) {
;             __builtin_amdgcn_fence(__ATOMIC_RELEASE, "agent");
;             asm volatile("s_waitcnt vmcnt(0)" ::: "memory");
;             const unsigned og = xb_add(&bar[XB_TOP], 1u);
;             const unsigned tg = og / nx;
;             if (og + 1u == (tg + 1u) * nx) xb_add(&bar[XB_TOPGEN], 1u);
;             else XB_SPIN(xb_ld(&bar[XB_TOPGEN]) == tg, bar);
;             __builtin_amdgcn_fence(__ATOMIC_ACQUIRE, "agent");
;             xb_add(&bar[XB_XGEN(b.x)], 1u);
;             asm volatile("s_waitcnt vmcnt(0)" ::: "memory");
;         } else {
;             XB_SPIN(xb_ld(&bar[XB_XGEN(b.x)]) == gen, bar);
;             __builtin_amdgcn_fence(__ATOMIC_ACQUIRE, "agent");
;             asm volatile("s_waitcnt vmcnt(0)" ::: "memory");
;         }
.LBB0_976:
	s_cmp_gt_i32 s75, 6
	s_cselect_b64 s[2:3], -1, 0
	s_and_b64 s[0:1], s[0:1], s[2:3]
	s_andn2_b64 vcc, exec, s[0:1]
	s_cbranch_vccnz .LBB0_1030
	s_waitcnt vmcnt(0)
	s_waitcnt vmcnt(0) lgkmcnt(0)
	s_barrier
	v_readfirstlane_b32 s4, v188
	s_lshr_b32 s4, s4, 6
	s_cmp_eq_u32 s4, 1
	s_cbranch_scc0 .Lmy_w1_5
	buffer_inv sc1
	s_waitcnt vmcnt(0)
.Lmy_w1_5:
	s_mov_b64 s[0:1], exec
	v_readlane_b32 s4, v254, 9
	v_readlane_b32 s5, v254, 10
	s_and_b64 s[4:5], s[0:1], s[4:5]
	s_mov_b64 exec, s[4:5]
	s_cbranch_execz .LBB0_1029
	s_cmp_eq_u32 s74, 5
	s_cbranch_scc1 .Lmy_fb_5_orig
	s_add_i32 s4, 0, 0x26700
	v_mov_b32_e32 v0, s4
	ds_read2_b32 v[2:3], v0 offset1:1
	s_lshl_b32 s4, s88, 8
	s_add_u32 s4, s72, s4
	s_addc_u32 s5, s73, 0
	v_mov_b32_e32 v4, 0x1000
	v_mov_b32_e32 v5, 1
	global_atomic_add v4, v4, v5, s[4:5] offset:1024 sc0
	s_sub_i32 s6, 6, s74
	s_waitcnt lgkmcnt(0)
	v_readfirstlane_b32 s7, v2
	v_readfirstlane_b32 s8, v3
	s_mul_i32 s7, s7, s6
	s_add_i32 s6, s6, -1
	s_mul_i32 s8, s8, s6
	s_add_i32 s8, s8, 1
	v_mov_b32_e32 v6, 0x2000
	s_waitcnt vmcnt(0)
	v_readfirstlane_b32 s10, v4
	s_add_i32 s10, s10, 1
	s_cmp_lg_u32 s10, s7
	s_cbranch_scc1 .Lmy_fb_5_wait
	buffer_wbl2 sc1
	s_mov_b64 s[10:11], exec
	s_mov_b64 exec, 0xffff
	v_mbcnt_lo_u32_b32 v7, -1, 0
	v_lshlrev_b32_e32 v7, 8, v7
	v_add_u32_e32 v7, 0x2400, v7
	v_mov_b32_e32 v8, 1
	s_waitcnt vmcnt(0)
	global_atomic_add v7, v8, s[72:73]
	s_mov_b64 exec, s[10:11]
